# s_setprio trimming: the back-to-back 'setprio 0; setprio 1' pairs between the two MFMA blocks of a super-phase removed in the four GEMM K-loops
# speedup vs baseline: 1.0100x; 1.0100x over previous
.LBB0_589:
	s_add_u32 s40, s38, 0xfff80080
	s_addc_u32 s41, s39, -1
	s_cmp_eq_u32 s60, 28
	s_cselect_b32 s43, s11, s41
	s_cselect_b32 s42, s56, s40
	s_cselect_b32 s41, s15, s59
	s_cselect_b32 s40, s57, s58
	s_add_i32 s61, 0, 0x10000
	v_add_u32_e32 v34, s61, v213
	s_add_i32 s64, 0, 0x14000
	ds_read_b128 v[132:135], v34
	ds_read_b128 v[136:139], v34 offset:1024
	ds_read_b128 v[140:143], v34 offset:2048
	ds_read_b128 v[144:147], v34 offset:3072
	v_add_u32_e32 v34, s64, v213
	ds_read_b128 v[148:151], v34
	ds_read_b128 v[152:155], v34 offset:1024
	ds_read_b128 v[156:159], v34 offset:2048
	ds_read_b128 v[160:163], v34 offset:3072
	v_lshl_add_u64 v[184:185], s[38:39], 0, v[198:199]
	s_add_i32 m0, s47, 0xc000
	ds_read_b128 v[164:167], v219
	ds_read_b128 v[168:171], v219 offset:1024
	ds_read_b128 v[172:175], v219 offset:2048
	ds_read_b128 v[176:179], v219 offset:3072
	ds_read_b128 v[202:205], v219 offset:4096
	ds_read_b128 v[206:209], v219 offset:5120
	ds_read_b128 v[220:223], v219 offset:6144
	ds_read_b128 v[224:227], v219 offset:7168
	global_load_lds_dwordx4 v[184:185], off
	v_lshl_add_u64 v[184:185], s[38:39], 0, v[200:201]
	s_add_i32 m0, s47, 0xe000
	s_nop 0
	global_load_lds_dwordx4 v[184:185], off
	s_waitcnt vmcnt(8)
	s_waitcnt lgkmcnt(0)
	s_barrier
	s_setprio 1
	s_waitcnt lgkmcnt(0)
	v_mfma_f32_16x16x32_bf16 v[128:131], v[132:135], v[164:167], v[128:131]
	v_mfma_f32_16x16x32_bf16 v[124:127], v[140:143], v[164:167], v[124:127]
	v_mfma_f32_16x16x32_bf16 v[112:115], v[132:135], v[172:175], v[112:115]
	v_mfma_f32_16x16x32_bf16 v[108:111], v[140:143], v[172:175], v[108:111]
	v_mfma_f32_16x16x32_bf16 v[96:99], v[132:135], v[202:205], v[96:99]
	v_mfma_f32_16x16x32_bf16 v[92:95], v[140:143], v[202:205], v[92:95]
	v_mfma_f32_16x16x32_bf16 v[80:83], v[132:135], v[220:223], v[80:83]
	v_mfma_f32_16x16x32_bf16 v[76:79], v[140:143], v[220:223], v[76:79]
	v_mfma_f32_16x16x32_bf16 v[128:131], v[136:139], v[168:171], v[128:131]
	v_mfma_f32_16x16x32_bf16 v[124:127], v[144:147], v[168:171], v[124:127]
	v_mfma_f32_16x16x32_bf16 v[112:115], v[136:139], v[176:179], v[112:115]
	v_mfma_f32_16x16x32_bf16 v[108:111], v[144:147], v[176:179], v[108:111]
	v_mfma_f32_16x16x32_bf16 v[96:99], v[136:139], v[206:209], v[96:99]
	v_mfma_f32_16x16x32_bf16 v[92:95], v[144:147], v[206:209], v[92:95]
	v_mfma_f32_16x16x32_bf16 v[80:83], v[136:139], v[224:227], v[80:83]
	v_mfma_f32_16x16x32_bf16 v[76:79], v[144:147], v[224:227], v[76:79]
	v_mfma_f32_16x16x32_bf16 v[120:123], v[148:151], v[164:167], v[120:123]
	v_mfma_f32_16x16x32_bf16 v[116:119], v[156:159], v[164:167], v[116:119]
	v_mfma_f32_16x16x32_bf16 v[104:107], v[148:151], v[172:175], v[104:107]
	v_mfma_f32_16x16x32_bf16 v[100:103], v[156:159], v[172:175], v[100:103]
	v_mfma_f32_16x16x32_bf16 v[88:91], v[148:151], v[202:205], v[88:91]
	v_mfma_f32_16x16x32_bf16 v[84:87], v[156:159], v[202:205], v[84:87]
	v_mfma_f32_16x16x32_bf16 v[72:75], v[148:151], v[220:223], v[72:75]
	v_mfma_f32_16x16x32_bf16 v[68:71], v[156:159], v[220:223], v[68:71]
	v_mfma_f32_16x16x32_bf16 v[120:123], v[152:155], v[168:171], v[120:123]
	v_mfma_f32_16x16x32_bf16 v[116:119], v[160:163], v[168:171], v[116:119]
	v_mfma_f32_16x16x32_bf16 v[104:107], v[152:155], v[176:179], v[104:107]
	v_mfma_f32_16x16x32_bf16 v[100:103], v[160:163], v[176:179], v[100:103]
	v_mfma_f32_16x16x32_bf16 v[88:91], v[152:155], v[206:209], v[88:91]
	v_mfma_f32_16x16x32_bf16 v[84:87], v[160:163], v[206:209], v[84:87]
	v_mfma_f32_16x16x32_bf16 v[72:75], v[152:155], v[224:227], v[72:75]
	v_mfma_f32_16x16x32_bf16 v[68:71], v[160:163], v[224:227], v[68:71]
	s_setprio 0
	s_barrier
	s_add_i32 s61, s61, s46
	v_lshl_add_u64 v[184:185], s[40:41], 0, v[190:191]
	s_mov_b32 m0, s61
	ds_read_b128 v[164:167], v219 offset:16384
	ds_read_b128 v[168:171], v219 offset:17408
	ds_read_b128 v[172:175], v219 offset:18432
	ds_read_b128 v[176:179], v219 offset:19456
	ds_read_b128 v[202:205], v219 offset:20480
	ds_read_b128 v[206:209], v219 offset:21504
	ds_read_b128 v[220:223], v219 offset:22528
	ds_read_b128 v[224:227], v219 offset:23552
	global_load_lds_dwordx4 v[184:185], off
	s_add_i32 m0, s61, 0x2000
	s_add_u32 s62, s40, 0x80000
	v_lshl_add_u64 v[186:187], s[40:41], 0, v[180:181]
	s_addc_u32 s63, s41, 0
	s_add_i32 s61, s64, s46
	global_load_lds_dwordx4 v[186:187], off
	v_lshl_add_u64 v[188:189], s[62:63], 0, v[190:191]
	s_mov_b32 m0, s61
	v_lshl_add_u64 v[210:211], s[42:43], 0, v[182:183]
	global_load_lds_dwordx4 v[188:189], off
	v_lshl_add_u64 v[188:189], s[62:63], 0, v[180:181]
	s_add_i32 m0, s61, 0x2000
	s_nop 0
	global_load_lds_dwordx4 v[188:189], off
	v_lshl_add_u64 v[188:189], s[42:43], 0, v[192:193]
	s_mov_b32 m0, s47
	s_nop 0
	global_load_lds_dwordx4 v[188:189], off
	s_mov_b32 m0, s48
	s_nop 0
	global_load_lds_dwordx4 v[210:211], off
	s_waitcnt vmcnt(8)
	s_waitcnt lgkmcnt(0)
	s_barrier
	s_setprio 1
	s_waitcnt lgkmcnt(0)
	v_mfma_f32_16x16x32_bf16 v[64:67], v[132:135], v[164:167], v[64:67]
	v_mfma_f32_16x16x32_bf16 v[60:63], v[140:143], v[164:167], v[60:63]
	v_mfma_f32_16x16x32_bf16 v[48:51], v[132:135], v[172:175], v[48:51]
	v_mfma_f32_16x16x32_bf16 v[44:47], v[140:143], v[172:175], v[44:47]
	v_mfma_f32_16x16x32_bf16 v[30:33], v[132:135], v[202:205], v[30:33]
	v_mfma_f32_16x16x32_bf16 v[26:29], v[140:143], v[202:205], v[26:29]
	v_mfma_f32_16x16x32_bf16 v[14:17], v[132:135], v[220:223], v[14:17]
	v_mfma_f32_16x16x32_bf16 v[10:13], v[140:143], v[220:223], v[10:13]
	v_mfma_f32_16x16x32_bf16 v[64:67], v[136:139], v[168:171], v[64:67]
	v_mfma_f32_16x16x32_bf16 v[60:63], v[144:147], v[168:171], v[60:63]
	v_mfma_f32_16x16x32_bf16 v[48:51], v[136:139], v[176:179], v[48:51]
	v_mfma_f32_16x16x32_bf16 v[44:47], v[144:147], v[176:179], v[44:47]
	v_mfma_f32_16x16x32_bf16 v[30:33], v[136:139], v[206:209], v[30:33]
	v_mfma_f32_16x16x32_bf16 v[26:29], v[144:147], v[206:209], v[26:29]
	v_mfma_f32_16x16x32_bf16 v[14:17], v[136:139], v[224:227], v[14:17]
	v_mfma_f32_16x16x32_bf16 v[10:13], v[144:147], v[224:227], v[10:13]
	v_mfma_f32_16x16x32_bf16 v[56:59], v[148:151], v[164:167], v[56:59]
	v_mfma_f32_16x16x32_bf16 v[52:55], v[156:159], v[164:167], v[52:55]
	v_mfma_f32_16x16x32_bf16 v[40:43], v[148:151], v[172:175], v[40:43]
	v_mfma_f32_16x16x32_bf16 v[36:39], v[156:159], v[172:175], v[36:39]
	v_mfma_f32_16x16x32_bf16 v[22:25], v[148:151], v[202:205], v[22:25]
	v_mfma_f32_16x16x32_bf16 v[18:21], v[156:159], v[202:205], v[18:21]
	v_mfma_f32_16x16x32_bf16 v[6:9], v[148:151], v[220:223], v[6:9]
	v_mfma_f32_16x16x32_bf16 v[2:5], v[156:159], v[220:223], v[2:5]
	v_mfma_f32_16x16x32_bf16 v[56:59], v[152:155], v[168:171], v[56:59]
	v_mfma_f32_16x16x32_bf16 v[52:55], v[160:163], v[168:171], v[52:55]
	v_mfma_f32_16x16x32_bf16 v[40:43], v[152:155], v[176:179], v[40:43]
	v_mfma_f32_16x16x32_bf16 v[36:39], v[160:163], v[176:179], v[36:39]
	v_mfma_f32_16x16x32_bf16 v[22:25], v[152:155], v[206:209], v[22:25]
	v_mfma_f32_16x16x32_bf16 v[18:21], v[160:163], v[206:209], v[18:21]
	v_mfma_f32_16x16x32_bf16 v[6:9], v[152:155], v[224:227], v[6:9]
	v_mfma_f32_16x16x32_bf16 v[2:5], v[160:163], v[224:227], v[2:5]
	s_setprio 0
	s_barrier
	s_add_i32 s61, 0, 0x18000
	v_add_u32_e32 v34, s61, v213
	s_add_i32 s62, 0, 0x1c000
	ds_read_b128 v[132:135], v34
	ds_read_b128 v[136:139], v34 offset:1024
	ds_read_b128 v[140:143], v34 offset:2048
	ds_read_b128 v[144:147], v34 offset:3072
	v_add_u32_e32 v34, s62, v213
	ds_read_b128 v[148:151], v34
	ds_read_b128 v[152:155], v34 offset:1024
	ds_read_b128 v[156:159], v34 offset:2048
	ds_read_b128 v[160:163], v34 offset:3072
	s_add_u32 s42, s42, 0x80000
	s_addc_u32 s43, s43, 0
	s_mov_b32 m0, s49
	v_lshl_add_u64 v[228:229], s[42:43], 0, v[192:193]
	ds_read_b128 v[164:167], v219 offset:32768
	ds_read_b128 v[168:171], v219 offset:33792
	ds_read_b128 v[172:175], v219 offset:34816
	ds_read_b128 v[176:179], v219 offset:35840
	ds_read_b128 v[202:205], v219 offset:36864
	ds_read_b128 v[206:209], v219 offset:37888
	ds_read_b128 v[220:223], v219 offset:38912
	ds_read_b128 v[224:227], v219 offset:39936
	global_load_lds_dwordx4 v[228:229], off
	v_lshl_add_u64 v[228:229], s[42:43], 0, v[182:183]
	s_mov_b32 m0, s50
	s_nop 0
	global_load_lds_dwordx4 v[228:229], off
	s_waitcnt vmcnt(8)
	s_waitcnt lgkmcnt(0)
	s_barrier
	s_setprio 1
	s_waitcnt lgkmcnt(0)
	v_mfma_f32_16x16x32_bf16 v[128:131], v[132:135], v[164:167], v[128:131]
	v_mfma_f32_16x16x32_bf16 v[124:127], v[140:143], v[164:167], v[124:127]
	v_mfma_f32_16x16x32_bf16 v[112:115], v[132:135], v[172:175], v[112:115]
	v_mfma_f32_16x16x32_bf16 v[108:111], v[140:143], v[172:175], v[108:111]
	v_mfma_f32_16x16x32_bf16 v[96:99], v[132:135], v[202:205], v[96:99]
	v_mfma_f32_16x16x32_bf16 v[92:95], v[140:143], v[202:205], v[92:95]
	v_mfma_f32_16x16x32_bf16 v[80:83], v[132:135], v[220:223], v[80:83]
	v_mfma_f32_16x16x32_bf16 v[76:79], v[140:143], v[220:223], v[76:79]
	v_mfma_f32_16x16x32_bf16 v[128:131], v[136:139], v[168:171], v[128:131]
	v_mfma_f32_16x16x32_bf16 v[124:127], v[144:147], v[168:171], v[124:127]
	v_mfma_f32_16x16x32_bf16 v[112:115], v[136:139], v[176:179], v[112:115]
	v_mfma_f32_16x16x32_bf16 v[108:111], v[144:147], v[176:179], v[108:111]
	v_mfma_f32_16x16x32_bf16 v[96:99], v[136:139], v[206:209], v[96:99]
	v_mfma_f32_16x16x32_bf16 v[92:95], v[144:147], v[206:209], v[92:95]
	v_mfma_f32_16x16x32_bf16 v[80:83], v[136:139], v[224:227], v[80:83]
	v_mfma_f32_16x16x32_bf16 v[76:79], v[144:147], v[224:227], v[76:79]
	v_mfma_f32_16x16x32_bf16 v[120:123], v[148:151], v[164:167], v[120:123]
	v_mfma_f32_16x16x32_bf16 v[116:119], v[156:159], v[164:167], v[116:119]
	v_mfma_f32_16x16x32_bf16 v[104:107], v[148:151], v[172:175], v[104:107]
	v_mfma_f32_16x16x32_bf16 v[100:103], v[156:159], v[172:175], v[100:103]
	v_mfma_f32_16x16x32_bf16 v[88:91], v[148:151], v[202:205], v[88:91]
	v_mfma_f32_16x16x32_bf16 v[84:87], v[156:159], v[202:205], v[84:87]
	v_mfma_f32_16x16x32_bf16 v[72:75], v[148:151], v[220:223], v[72:75]
	v_mfma_f32_16x16x32_bf16 v[68:71], v[156:159], v[220:223], v[68:71]
	v_mfma_f32_16x16x32_bf16 v[120:123], v[152:155], v[168:171], v[120:123]
	v_mfma_f32_16x16x32_bf16 v[116:119], v[160:163], v[168:171], v[116:119]
	v_mfma_f32_16x16x32_bf16 v[104:107], v[152:155], v[176:179], v[104:107]
	v_mfma_f32_16x16x32_bf16 v[100:103], v[160:163], v[176:179], v[100:103]
	v_mfma_f32_16x16x32_bf16 v[88:91], v[152:155], v[206:209], v[88:91]
	v_mfma_f32_16x16x32_bf16 v[84:87], v[160:163], v[206:209], v[84:87]
	v_mfma_f32_16x16x32_bf16 v[72:75], v[152:155], v[224:227], v[72:75]
	v_mfma_f32_16x16x32_bf16 v[68:71], v[160:163], v[224:227], v[68:71]
	s_setprio 0
	s_barrier
	s_add_i32 s42, s61, s46
	v_lshl_add_u64 v[184:185], v[184:185], 0, s[96:97]
	s_mov_b32 m0, s42
	ds_read_b128 v[164:167], v219 offset:49152
	ds_read_b128 v[168:171], v219 offset:50176
	ds_read_b128 v[172:175], v219 offset:51200
	ds_read_b128 v[176:179], v219 offset:52224
	ds_read_b128 v[202:205], v219 offset:53248
	ds_read_b128 v[206:209], v219 offset:54272
	ds_read_b128 v[220:223], v219 offset:55296
	ds_read_b128 v[224:227], v219 offset:56320
	global_load_lds_dwordx4 v[184:185], off
	s_add_i32 m0, s42, 0x2000
	s_add_u32 s40, s40, 0x80080
	v_lshl_add_u64 v[184:185], v[186:187], 0, s[96:97]
	s_addc_u32 s41, s41, 0
	s_add_i32 s42, s62, s46
	global_load_lds_dwordx4 v[184:185], off
	v_lshl_add_u64 v[184:185], s[40:41], 0, v[190:191]
	s_mov_b32 m0, s42
	s_nop 0
	global_load_lds_dwordx4 v[184:185], off
	v_lshl_add_u64 v[184:185], s[40:41], 0, v[180:181]
	s_add_i32 m0, s42, 0x2000
	s_nop 0
	global_load_lds_dwordx4 v[184:185], off
	v_lshl_add_u64 v[184:185], v[188:189], 0, s[96:97]
	s_mov_b32 m0, s51
	s_nop 0
	global_load_lds_dwordx4 v[184:185], off
	v_lshl_add_u64 v[184:185], v[210:211], 0, s[96:97]
	s_mov_b32 m0, s52
	s_nop 0
	global_load_lds_dwordx4 v[184:185], off
	s_waitcnt vmcnt(8)
	s_waitcnt lgkmcnt(0)
	s_barrier
	s_setprio 1
	s_waitcnt lgkmcnt(0)
	v_mfma_f32_16x16x32_bf16 v[64:67], v[132:135], v[164:167], v[64:67]
	v_mfma_f32_16x16x32_bf16 v[60:63], v[140:143], v[164:167], v[60:63]
	v_mfma_f32_16x16x32_bf16 v[48:51], v[132:135], v[172:175], v[48:51]
	v_mfma_f32_16x16x32_bf16 v[44:47], v[140:143], v[172:175], v[44:47]
	v_mfma_f32_16x16x32_bf16 v[30:33], v[132:135], v[202:205], v[30:33]
	v_mfma_f32_16x16x32_bf16 v[26:29], v[140:143], v[202:205], v[26:29]
	v_mfma_f32_16x16x32_bf16 v[14:17], v[132:135], v[220:223], v[14:17]
	v_mfma_f32_16x16x32_bf16 v[10:13], v[140:143], v[220:223], v[10:13]
	v_mfma_f32_16x16x32_bf16 v[64:67], v[136:139], v[168:171], v[64:67]
	v_mfma_f32_16x16x32_bf16 v[60:63], v[144:147], v[168:171], v[60:63]
	v_mfma_f32_16x16x32_bf16 v[48:51], v[136:139], v[176:179], v[48:51]
	v_mfma_f32_16x16x32_bf16 v[44:47], v[144:147], v[176:179], v[44:47]
	v_mfma_f32_16x16x32_bf16 v[30:33], v[136:139], v[206:209], v[30:33]
	v_mfma_f32_16x16x32_bf16 v[26:29], v[144:147], v[206:209], v[26:29]
	v_mfma_f32_16x16x32_bf16 v[14:17], v[136:139], v[224:227], v[14:17]
	v_mfma_f32_16x16x32_bf16 v[10:13], v[144:147], v[224:227], v[10:13]
	v_mfma_f32_16x16x32_bf16 v[56:59], v[148:151], v[164:167], v[56:59]
	v_mfma_f32_16x16x32_bf16 v[52:55], v[156:159], v[164:167], v[52:55]
	v_mfma_f32_16x16x32_bf16 v[40:43], v[148:151], v[172:175], v[40:43]
	v_mfma_f32_16x16x32_bf16 v[36:39], v[156:159], v[172:175], v[36:39]
	v_mfma_f32_16x16x32_bf16 v[22:25], v[148:151], v[202:205], v[22:25]
	v_mfma_f32_16x16x32_bf16 v[18:21], v[156:159], v[202:205], v[18:21]
	v_mfma_f32_16x16x32_bf16 v[6:9], v[148:151], v[220:223], v[6:9]
	v_mfma_f32_16x16x32_bf16 v[2:5], v[156:159], v[220:223], v[2:5]
	v_mfma_f32_16x16x32_bf16 v[56:59], v[152:155], v[168:171], v[56:59]
	v_mfma_f32_16x16x32_bf16 v[52:55], v[160:163], v[168:171], v[52:55]
	v_mfma_f32_16x16x32_bf16 v[40:43], v[152:155], v[176:179], v[40:43]
	v_mfma_f32_16x16x32_bf16 v[36:39], v[160:163], v[176:179], v[36:39]
	v_mfma_f32_16x16x32_bf16 v[22:25], v[152:155], v[206:209], v[22:25]
	v_mfma_f32_16x16x32_bf16 v[18:21], v[160:163], v[206:209], v[18:21]
	v_mfma_f32_16x16x32_bf16 v[6:9], v[152:155], v[224:227], v[6:9]
	v_mfma_f32_16x16x32_bf16 v[2:5], v[160:163], v[224:227], v[2:5]
	s_setprio 0
	s_barrier
	s_add_i32 s60, s60, 2
	s_add_u32 s38, s38, 0x100
	s_addc_u32 s39, s39, 0
	s_add_u32 s58, s58, 0x100
	s_addc_u32 s59, s59, 0
	s_cmp_gt_u32 s60, 29
	s_cbranch_scc0 .LBB0_589
	s_and_b64 vcc, exec, s[8:9]
	s_cbranch_vccz .LBB0_592
	s_barrier

.LBB0_1248:
	s_add_u32 s45, s8, s54
	s_addc_u32 s47, s9, s55
	s_add_u32 s56, s10, s54
	s_addc_u32 s57, s11, s55
	s_cmp_eq_u32 s61, s43
	s_cselect_b32 s59, s51, s47
	s_cselect_b32 s58, s50, s45
	s_cselect_b32 s57, s53, s57
	s_cselect_b32 s56, s52, s56
	s_add_i32 s45, 0, 0x10000
	s_add_i32 s47, 0, 0x14000
	v_add_u32_e32 v154, s45, v185
	v_add_u32_e32 v170, s47, v185
	ds_read_b128 v[136:139], v154
	ds_read_b128 v[140:143], v154 offset:1024
	ds_read_b128 v[144:147], v154 offset:2048
	ds_read_b128 v[154:157], v154 offset:3072
	ds_read_b128 v[158:161], v170
	ds_read_b128 v[162:165], v170 offset:1024
	ds_read_b128 v[166:169], v170 offset:2048
	ds_read_b128 v[170:173], v170 offset:3072
	v_lshl_add_u64 v[182:183], s[8:9], 0, v[134:135]
	s_add_i32 m0, s1, 0xc000
	ds_read_b128 v[174:177], v203
	ds_read_b128 v[178:181], v203 offset:1024
	ds_read_b128 v[186:189], v203 offset:2048
	ds_read_b128 v[190:193], v203 offset:3072
	ds_read_b128 v[194:197], v203 offset:4096
	ds_read_b128 v[198:201], v203 offset:5120
	ds_read_b128 v[204:207], v203 offset:6144
	ds_read_b128 v[208:211], v203 offset:7168
	global_load_lds_dwordx4 v[182:183], off
	v_lshl_add_u64 v[182:183], s[8:9], 0, v[132:133]
	s_add_i32 m0, s1, 0xe000
	s_nop 0
	global_load_lds_dwordx4 v[182:183], off
	s_waitcnt vmcnt(8)
	s_waitcnt lgkmcnt(0)
	s_barrier
	s_setprio 1
	s_waitcnt lgkmcnt(0)
	v_mfma_f32_16x16x32_bf16 v[128:131], v[136:139], v[174:177], v[128:131]
	v_mfma_f32_16x16x32_bf16 v[124:127], v[144:147], v[174:177], v[124:127]
	v_mfma_f32_16x16x32_bf16 v[120:123], v[136:139], v[186:189], v[120:123]
	v_mfma_f32_16x16x32_bf16 v[116:119], v[144:147], v[186:189], v[116:119]
	v_mfma_f32_16x16x32_bf16 v[112:115], v[136:139], v[194:197], v[112:115]
	v_mfma_f32_16x16x32_bf16 v[108:111], v[144:147], v[194:197], v[108:111]
	v_mfma_f32_16x16x32_bf16 v[104:107], v[136:139], v[204:207], v[104:107]
	v_mfma_f32_16x16x32_bf16 v[100:103], v[144:147], v[204:207], v[100:103]
	v_mfma_f32_16x16x32_bf16 v[128:131], v[140:143], v[178:181], v[128:131]
	v_mfma_f32_16x16x32_bf16 v[124:127], v[154:157], v[178:181], v[124:127]
	v_mfma_f32_16x16x32_bf16 v[120:123], v[140:143], v[190:193], v[120:123]
	v_mfma_f32_16x16x32_bf16 v[116:119], v[154:157], v[190:193], v[116:119]
	v_mfma_f32_16x16x32_bf16 v[112:115], v[140:143], v[198:201], v[112:115]
	v_mfma_f32_16x16x32_bf16 v[108:111], v[154:157], v[198:201], v[108:111]
	v_mfma_f32_16x16x32_bf16 v[104:107], v[140:143], v[208:211], v[104:107]
	v_mfma_f32_16x16x32_bf16 v[100:103], v[154:157], v[208:211], v[100:103]
	v_mfma_f32_16x16x32_bf16 v[96:99], v[158:161], v[174:177], v[96:99]
	v_mfma_f32_16x16x32_bf16 v[92:95], v[166:169], v[174:177], v[92:95]
	v_mfma_f32_16x16x32_bf16 v[88:91], v[158:161], v[186:189], v[88:91]
	v_mfma_f32_16x16x32_bf16 v[84:87], v[166:169], v[186:189], v[84:87]
	v_mfma_f32_16x16x32_bf16 v[80:83], v[158:161], v[194:197], v[80:83]
	v_mfma_f32_16x16x32_bf16 v[76:79], v[166:169], v[194:197], v[76:79]
	v_mfma_f32_16x16x32_bf16 v[72:75], v[158:161], v[204:207], v[72:75]
	v_mfma_f32_16x16x32_bf16 v[68:71], v[166:169], v[204:207], v[68:71]
	v_mfma_f32_16x16x32_bf16 v[96:99], v[162:165], v[178:181], v[96:99]
	v_mfma_f32_16x16x32_bf16 v[92:95], v[170:173], v[178:181], v[92:95]
	v_mfma_f32_16x16x32_bf16 v[88:91], v[162:165], v[190:193], v[88:91]
	v_mfma_f32_16x16x32_bf16 v[84:87], v[170:173], v[190:193], v[84:87]
	v_mfma_f32_16x16x32_bf16 v[80:83], v[162:165], v[198:201], v[80:83]
	v_mfma_f32_16x16x32_bf16 v[76:79], v[170:173], v[198:201], v[76:79]
	v_mfma_f32_16x16x32_bf16 v[72:75], v[162:165], v[208:211], v[72:75]
	v_mfma_f32_16x16x32_bf16 v[68:71], v[170:173], v[208:211], v[68:71]
	s_setprio 0
	s_barrier
	s_add_i32 s45, s45, s62
	v_lshl_add_u64 v[182:183], s[56:57], 0, v[34:35]
	s_mov_b32 m0, s45
	ds_read_b128 v[174:177], v203 offset:16384
	ds_read_b128 v[178:181], v203 offset:17408
	ds_read_b128 v[186:189], v203 offset:18432
	ds_read_b128 v[190:193], v203 offset:19456
	ds_read_b128 v[194:197], v203 offset:20480
	ds_read_b128 v[198:201], v203 offset:21504
	ds_read_b128 v[204:207], v203 offset:22528
	ds_read_b128 v[208:211], v203 offset:23552
	global_load_lds_dwordx4 v[182:183], off
	s_add_i32 m0, s45, 0x2000
	s_add_u32 vcc_lo, s56, 0x80000
	v_lshl_add_u64 v[212:213], s[56:57], 0, v[148:149]
	s_addc_u32 vcc_hi, s57, 0
	s_add_i32 s45, s47, s62
	global_load_lds_dwordx4 v[212:213], off
	v_lshl_add_u64 v[214:215], vcc, 0, v[34:35]
	s_mov_b32 m0, s45
	v_lshl_add_u64 v[216:217], s[58:59], 0, v[148:149]
	global_load_lds_dwordx4 v[214:215], off
	v_lshl_add_u64 v[214:215], vcc, 0, v[148:149]
	s_add_i32 m0, s45, 0x2000
	s_nop 0
	global_load_lds_dwordx4 v[214:215], off
	v_lshl_add_u64 v[214:215], s[58:59], 0, v[34:35]
	s_mov_b32 m0, s1
	s_nop 0
	global_load_lds_dwordx4 v[214:215], off
	s_mov_b32 m0, s7
	s_nop 0
	global_load_lds_dwordx4 v[216:217], off
	s_waitcnt vmcnt(8)
	s_waitcnt lgkmcnt(0)
	s_barrier
	s_setprio 1
	s_waitcnt lgkmcnt(0)
	v_mfma_f32_16x16x32_bf16 v[64:67], v[136:139], v[174:177], v[64:67]
	v_mfma_f32_16x16x32_bf16 v[60:63], v[144:147], v[174:177], v[60:63]
	v_mfma_f32_16x16x32_bf16 v[56:59], v[136:139], v[186:189], v[56:59]
	v_mfma_f32_16x16x32_bf16 v[52:55], v[144:147], v[186:189], v[52:55]
	v_mfma_f32_16x16x32_bf16 v[48:51], v[136:139], v[194:197], v[48:51]
	v_mfma_f32_16x16x32_bf16 v[44:47], v[144:147], v[194:197], v[44:47]
	v_mfma_f32_16x16x32_bf16 v[40:43], v[136:139], v[204:207], v[40:43]
	v_mfma_f32_16x16x32_bf16 v[36:39], v[144:147], v[204:207], v[36:39]
	v_mfma_f32_16x16x32_bf16 v[64:67], v[140:143], v[178:181], v[64:67]
	v_mfma_f32_16x16x32_bf16 v[60:63], v[154:157], v[178:181], v[60:63]
	v_mfma_f32_16x16x32_bf16 v[56:59], v[140:143], v[190:193], v[56:59]
	v_mfma_f32_16x16x32_bf16 v[52:55], v[154:157], v[190:193], v[52:55]
	v_mfma_f32_16x16x32_bf16 v[48:51], v[140:143], v[198:201], v[48:51]
	v_mfma_f32_16x16x32_bf16 v[44:47], v[154:157], v[198:201], v[44:47]
	v_mfma_f32_16x16x32_bf16 v[40:43], v[140:143], v[208:211], v[40:43]
	v_mfma_f32_16x16x32_bf16 v[36:39], v[154:157], v[208:211], v[36:39]
	v_mfma_f32_16x16x32_bf16 v[30:33], v[158:161], v[174:177], v[30:33]
	v_mfma_f32_16x16x32_bf16 v[26:29], v[166:169], v[174:177], v[26:29]
	v_mfma_f32_16x16x32_bf16 v[22:25], v[158:161], v[186:189], v[22:25]
	v_mfma_f32_16x16x32_bf16 v[18:21], v[166:169], v[186:189], v[18:21]
	v_mfma_f32_16x16x32_bf16 v[14:17], v[158:161], v[194:197], v[14:17]
	v_mfma_f32_16x16x32_bf16 v[10:13], v[166:169], v[194:197], v[10:13]
	v_mfma_f32_16x16x32_bf16 v[6:9], v[158:161], v[204:207], v[6:9]
	v_mfma_f32_16x16x32_bf16 v[2:5], v[166:169], v[204:207], v[2:5]
	v_mfma_f32_16x16x32_bf16 v[30:33], v[162:165], v[178:181], v[30:33]
	v_mfma_f32_16x16x32_bf16 v[26:29], v[170:173], v[178:181], v[26:29]
	v_mfma_f32_16x16x32_bf16 v[22:25], v[162:165], v[190:193], v[22:25]
	v_mfma_f32_16x16x32_bf16 v[18:21], v[170:173], v[190:193], v[18:21]
	v_mfma_f32_16x16x32_bf16 v[14:17], v[162:165], v[198:201], v[14:17]
	v_mfma_f32_16x16x32_bf16 v[10:13], v[170:173], v[198:201], v[10:13]
	v_mfma_f32_16x16x32_bf16 v[6:9], v[162:165], v[208:211], v[6:9]
	v_mfma_f32_16x16x32_bf16 v[2:5], v[170:173], v[208:211], v[2:5]
	s_setprio 0
	s_barrier
	s_add_i32 s45, 0, 0x18000
	s_add_i32 s47, 0, 0x1c000
	v_add_u32_e32 v154, s45, v185
	v_add_u32_e32 v170, s47, v185
	ds_read_b128 v[136:139], v154
	ds_read_b128 v[140:143], v154 offset:1024
	ds_read_b128 v[144:147], v154 offset:2048
	ds_read_b128 v[154:157], v154 offset:3072
	ds_read_b128 v[158:161], v170
	ds_read_b128 v[162:165], v170 offset:1024
	ds_read_b128 v[166:169], v170 offset:2048
	ds_read_b128 v[170:173], v170 offset:3072
	s_add_u32 s58, s58, 0x80000
	s_addc_u32 s59, s59, 0
	s_mov_b32 m0, s65
	v_lshl_add_u64 v[218:219], s[58:59], 0, v[34:35]
	ds_read_b128 v[174:177], v203 offset:32768
	ds_read_b128 v[178:181], v203 offset:33792
	ds_read_b128 v[186:189], v203 offset:34816
	ds_read_b128 v[190:193], v203 offset:35840
	ds_read_b128 v[194:197], v203 offset:36864
	ds_read_b128 v[198:201], v203 offset:37888
	ds_read_b128 v[204:207], v203 offset:38912
	ds_read_b128 v[208:211], v203 offset:39936
	global_load_lds_dwordx4 v[218:219], off
	v_lshl_add_u64 v[218:219], s[58:59], 0, v[148:149]
	s_mov_b32 m0, s66
	s_nop 0
	global_load_lds_dwordx4 v[218:219], off
	s_waitcnt vmcnt(8)
	s_waitcnt lgkmcnt(0)
	s_barrier
	s_setprio 1
	s_waitcnt lgkmcnt(0)
	v_mfma_f32_16x16x32_bf16 v[128:131], v[136:139], v[174:177], v[128:131]
	v_mfma_f32_16x16x32_bf16 v[124:127], v[144:147], v[174:177], v[124:127]
	v_mfma_f32_16x16x32_bf16 v[120:123], v[136:139], v[186:189], v[120:123]
	v_mfma_f32_16x16x32_bf16 v[116:119], v[144:147], v[186:189], v[116:119]
	v_mfma_f32_16x16x32_bf16 v[112:115], v[136:139], v[194:197], v[112:115]
	v_mfma_f32_16x16x32_bf16 v[108:111], v[144:147], v[194:197], v[108:111]
	v_mfma_f32_16x16x32_bf16 v[104:107], v[136:139], v[204:207], v[104:107]
	v_mfma_f32_16x16x32_bf16 v[100:103], v[144:147], v[204:207], v[100:103]
	v_mfma_f32_16x16x32_bf16 v[128:131], v[140:143], v[178:181], v[128:131]
	v_mfma_f32_16x16x32_bf16 v[124:127], v[154:157], v[178:181], v[124:127]
	v_mfma_f32_16x16x32_bf16 v[120:123], v[140:143], v[190:193], v[120:123]
	v_mfma_f32_16x16x32_bf16 v[116:119], v[154:157], v[190:193], v[116:119]
	v_mfma_f32_16x16x32_bf16 v[112:115], v[140:143], v[198:201], v[112:115]
	v_mfma_f32_16x16x32_bf16 v[108:111], v[154:157], v[198:201], v[108:111]
	v_mfma_f32_16x16x32_bf16 v[104:107], v[140:143], v[208:211], v[104:107]
	v_mfma_f32_16x16x32_bf16 v[100:103], v[154:157], v[208:211], v[100:103]
	v_mfma_f32_16x16x32_bf16 v[96:99], v[158:161], v[174:177], v[96:99]
	v_mfma_f32_16x16x32_bf16 v[92:95], v[166:169], v[174:177], v[92:95]
	v_mfma_f32_16x16x32_bf16 v[88:91], v[158:161], v[186:189], v[88:91]
	v_mfma_f32_16x16x32_bf16 v[84:87], v[166:169], v[186:189], v[84:87]
	v_mfma_f32_16x16x32_bf16 v[80:83], v[158:161], v[194:197], v[80:83]
	v_mfma_f32_16x16x32_bf16 v[76:79], v[166:169], v[194:197], v[76:79]
	v_mfma_f32_16x16x32_bf16 v[72:75], v[158:161], v[204:207], v[72:75]
	v_mfma_f32_16x16x32_bf16 v[68:71], v[166:169], v[204:207], v[68:71]
	v_mfma_f32_16x16x32_bf16 v[96:99], v[162:165], v[178:181], v[96:99]
	v_mfma_f32_16x16x32_bf16 v[92:95], v[170:173], v[178:181], v[92:95]
	v_mfma_f32_16x16x32_bf16 v[88:91], v[162:165], v[190:193], v[88:91]
	v_mfma_f32_16x16x32_bf16 v[84:87], v[170:173], v[190:193], v[84:87]
	v_mfma_f32_16x16x32_bf16 v[80:83], v[162:165], v[198:201], v[80:83]
	v_mfma_f32_16x16x32_bf16 v[76:79], v[170:173], v[198:201], v[76:79]
	v_mfma_f32_16x16x32_bf16 v[72:75], v[162:165], v[208:211], v[72:75]
	v_mfma_f32_16x16x32_bf16 v[68:71], v[170:173], v[208:211], v[68:71]
	s_setprio 0
	s_barrier
	s_add_i32 s45, s45, s62
	v_lshl_add_u64 v[182:183], v[182:183], 0, s[96:97]
	s_mov_b32 m0, s45
	ds_read_b128 v[174:177], v203 offset:49152
	ds_read_b128 v[178:181], v203 offset:50176
	ds_read_b128 v[186:189], v203 offset:51200
	ds_read_b128 v[190:193], v203 offset:52224
	ds_read_b128 v[194:197], v203 offset:53248
	ds_read_b128 v[198:201], v203 offset:54272
	ds_read_b128 v[204:207], v203 offset:55296
	ds_read_b128 v[208:211], v203 offset:56320
	global_load_lds_dwordx4 v[182:183], off
	s_add_i32 m0, s45, 0x2000
	s_add_u32 s56, s56, 0x80080
	v_lshl_add_u64 v[182:183], v[212:213], 0, s[96:97]
	s_addc_u32 s57, s57, 0
	s_add_i32 s45, s47, s62
	global_load_lds_dwordx4 v[182:183], off
	v_lshl_add_u64 v[182:183], s[56:57], 0, v[34:35]
	s_mov_b32 m0, s45
	s_nop 0
	global_load_lds_dwordx4 v[182:183], off
	v_lshl_add_u64 v[182:183], s[56:57], 0, v[148:149]
	s_add_i32 m0, s45, 0x2000
	s_nop 0
	global_load_lds_dwordx4 v[182:183], off
	v_lshl_add_u64 v[182:183], v[214:215], 0, s[96:97]
	s_mov_b32 m0, s68
	s_nop 0
	global_load_lds_dwordx4 v[182:183], off
	v_lshl_add_u64 v[182:183], v[216:217], 0, s[96:97]
	s_mov_b32 m0, s69
	s_nop 0
	global_load_lds_dwordx4 v[182:183], off
	s_waitcnt vmcnt(8)
	s_waitcnt lgkmcnt(0)
	s_barrier
	s_setprio 1
	s_waitcnt lgkmcnt(0)
	v_mfma_f32_16x16x32_bf16 v[64:67], v[136:139], v[174:177], v[64:67]
	v_mfma_f32_16x16x32_bf16 v[60:63], v[144:147], v[174:177], v[60:63]
	v_mfma_f32_16x16x32_bf16 v[56:59], v[136:139], v[186:189], v[56:59]
	v_mfma_f32_16x16x32_bf16 v[52:55], v[144:147], v[186:189], v[52:55]
	v_mfma_f32_16x16x32_bf16 v[48:51], v[136:139], v[194:197], v[48:51]
	v_mfma_f32_16x16x32_bf16 v[44:47], v[144:147], v[194:197], v[44:47]
	v_mfma_f32_16x16x32_bf16 v[40:43], v[136:139], v[204:207], v[40:43]
	v_mfma_f32_16x16x32_bf16 v[36:39], v[144:147], v[204:207], v[36:39]
	v_mfma_f32_16x16x32_bf16 v[64:67], v[140:143], v[178:181], v[64:67]
	v_mfma_f32_16x16x32_bf16 v[60:63], v[154:157], v[178:181], v[60:63]
	v_mfma_f32_16x16x32_bf16 v[56:59], v[140:143], v[190:193], v[56:59]
	v_mfma_f32_16x16x32_bf16 v[52:55], v[154:157], v[190:193], v[52:55]
	v_mfma_f32_16x16x32_bf16 v[48:51], v[140:143], v[198:201], v[48:51]
	v_mfma_f32_16x16x32_bf16 v[44:47], v[154:157], v[198:201], v[44:47]
	v_mfma_f32_16x16x32_bf16 v[40:43], v[140:143], v[208:211], v[40:43]
	v_mfma_f32_16x16x32_bf16 v[36:39], v[154:157], v[208:211], v[36:39]
	v_mfma_f32_16x16x32_bf16 v[30:33], v[158:161], v[174:177], v[30:33]
	v_mfma_f32_16x16x32_bf16 v[26:29], v[166:169], v[174:177], v[26:29]
	v_mfma_f32_16x16x32_bf16 v[22:25], v[158:161], v[186:189], v[22:25]
	v_mfma_f32_16x16x32_bf16 v[18:21], v[166:169], v[186:189], v[18:21]
	v_mfma_f32_16x16x32_bf16 v[14:17], v[158:161], v[194:197], v[14:17]
	v_mfma_f32_16x16x32_bf16 v[10:13], v[166:169], v[194:197], v[10:13]
	v_mfma_f32_16x16x32_bf16 v[6:9], v[158:161], v[204:207], v[6:9]
	v_mfma_f32_16x16x32_bf16 v[2:5], v[166:169], v[204:207], v[2:5]
	v_mfma_f32_16x16x32_bf16 v[30:33], v[162:165], v[178:181], v[30:33]
	v_mfma_f32_16x16x32_bf16 v[26:29], v[170:173], v[178:181], v[26:29]
	v_mfma_f32_16x16x32_bf16 v[22:25], v[162:165], v[190:193], v[22:25]
	v_mfma_f32_16x16x32_bf16 v[18:21], v[170:173], v[190:193], v[18:21]
	v_mfma_f32_16x16x32_bf16 v[14:17], v[162:165], v[198:201], v[14:17]
	v_mfma_f32_16x16x32_bf16 v[10:13], v[170:173], v[198:201], v[10:13]
	v_mfma_f32_16x16x32_bf16 v[6:9], v[162:165], v[208:211], v[6:9]
	v_mfma_f32_16x16x32_bf16 v[2:5], v[170:173], v[208:211], v[2:5]
	s_setprio 0
	s_barrier
	s_add_i32 s45, s43, 2
	s_add_u32 s54, s54, 0x100
	s_addc_u32 s55, s55, 0
	v_lshl_add_u64 v[134:135], v[134:135], 0, s[28:29]
	v_lshl_add_u64 v[132:133], v[132:133], 0, s[28:29]
	s_cmp_ge_i32 s43, s61
	s_mov_b32 s43, s45
	s_cbranch_scc0 .LBB0_1248
	s_and_b64 vcc, exec, s[16:17]
	s_cbranch_vccz .LBB0_1251
	s_barrier

.LBB0_1485:
	s_add_u32 s40, s18, 0xfff80080
	s_addc_u32 s41, s19, -1
	s_cmp_eq_u32 s60, 28
	s_cselect_b32 s43, s9, s41
	s_cselect_b32 s42, s56, s40
	s_cselect_b32 s41, s11, s59
	s_cselect_b32 s40, s57, s58
	s_add_i32 s61, 0, 0x10000
	v_add_u32_e32 v142, s61, v145
	s_add_i32 s64, 0, 0x14000
	ds_read_b128 v[148:151], v142
	ds_read_b128 v[152:155], v142 offset:1024
	ds_read_b128 v[156:159], v142 offset:2048
	ds_read_b128 v[160:163], v142 offset:3072
	v_add_u32_e32 v142, s64, v145
	ds_read_b128 v[164:167], v142
	ds_read_b128 v[168:171], v142 offset:1024
	ds_read_b128 v[172:175], v142 offset:2048
	ds_read_b128 v[176:179], v142 offset:3072
	v_lshl_add_u64 v[142:143], s[18:19], 0, v[138:139]
	s_add_i32 m0, s47, 0xc000
	ds_read_b128 v[180:183], v147
	ds_read_b128 v[184:187], v147 offset:1024
	ds_read_b128 v[188:191], v147 offset:2048
	ds_read_b128 v[192:195], v147 offset:3072
	ds_read_b128 v[196:199], v147 offset:4096
	ds_read_b128 v[200:203], v147 offset:5120
	ds_read_b128 v[204:207], v147 offset:6144
	ds_read_b128 v[208:211], v147 offset:7168
	global_load_lds_dwordx4 v[142:143], off
	v_lshl_add_u64 v[142:143], s[18:19], 0, v[140:141]
	s_add_i32 m0, s47, 0xe000
	s_nop 0
	global_load_lds_dwordx4 v[142:143], off
	s_waitcnt vmcnt(8)
	s_waitcnt lgkmcnt(0)
	s_barrier
	s_setprio 1
	s_waitcnt lgkmcnt(0)
	v_mfma_f32_16x16x32_bf16 v[128:131], v[148:151], v[180:183], v[128:131]
	v_mfma_f32_16x16x32_bf16 v[124:127], v[156:159], v[180:183], v[124:127]
	v_mfma_f32_16x16x32_bf16 v[112:115], v[148:151], v[188:191], v[112:115]
	v_mfma_f32_16x16x32_bf16 v[108:111], v[156:159], v[188:191], v[108:111]
	v_mfma_f32_16x16x32_bf16 v[96:99], v[148:151], v[196:199], v[96:99]
	v_mfma_f32_16x16x32_bf16 v[92:95], v[156:159], v[196:199], v[92:95]
	v_mfma_f32_16x16x32_bf16 v[80:83], v[148:151], v[204:207], v[80:83]
	v_mfma_f32_16x16x32_bf16 v[76:79], v[156:159], v[204:207], v[76:79]
	v_mfma_f32_16x16x32_bf16 v[128:131], v[152:155], v[184:187], v[128:131]
	v_mfma_f32_16x16x32_bf16 v[124:127], v[160:163], v[184:187], v[124:127]
	v_mfma_f32_16x16x32_bf16 v[112:115], v[152:155], v[192:195], v[112:115]
	v_mfma_f32_16x16x32_bf16 v[108:111], v[160:163], v[192:195], v[108:111]
	v_mfma_f32_16x16x32_bf16 v[96:99], v[152:155], v[200:203], v[96:99]
	v_mfma_f32_16x16x32_bf16 v[92:95], v[160:163], v[200:203], v[92:95]
	v_mfma_f32_16x16x32_bf16 v[80:83], v[152:155], v[208:211], v[80:83]
	v_mfma_f32_16x16x32_bf16 v[76:79], v[160:163], v[208:211], v[76:79]
	v_mfma_f32_16x16x32_bf16 v[120:123], v[164:167], v[180:183], v[120:123]
	v_mfma_f32_16x16x32_bf16 v[116:119], v[172:175], v[180:183], v[116:119]
	v_mfma_f32_16x16x32_bf16 v[104:107], v[164:167], v[188:191], v[104:107]
	v_mfma_f32_16x16x32_bf16 v[100:103], v[172:175], v[188:191], v[100:103]
	v_mfma_f32_16x16x32_bf16 v[88:91], v[164:167], v[196:199], v[88:91]
	v_mfma_f32_16x16x32_bf16 v[84:87], v[172:175], v[196:199], v[84:87]
	v_mfma_f32_16x16x32_bf16 v[72:75], v[164:167], v[204:207], v[72:75]
	v_mfma_f32_16x16x32_bf16 v[68:71], v[172:175], v[204:207], v[68:71]
	v_mfma_f32_16x16x32_bf16 v[120:123], v[168:171], v[184:187], v[120:123]
	v_mfma_f32_16x16x32_bf16 v[116:119], v[176:179], v[184:187], v[116:119]
	v_mfma_f32_16x16x32_bf16 v[104:107], v[168:171], v[192:195], v[104:107]
	v_mfma_f32_16x16x32_bf16 v[100:103], v[176:179], v[192:195], v[100:103]
	v_mfma_f32_16x16x32_bf16 v[88:91], v[168:171], v[200:203], v[88:91]
	v_mfma_f32_16x16x32_bf16 v[84:87], v[176:179], v[200:203], v[84:87]
	v_mfma_f32_16x16x32_bf16 v[72:75], v[168:171], v[208:211], v[72:75]
	v_mfma_f32_16x16x32_bf16 v[68:71], v[176:179], v[208:211], v[68:71]
	s_setprio 0
	s_barrier
	s_add_i32 s61, s61, s46
	v_lshl_add_u64 v[142:143], s[40:41], 0, v[34:35]
	s_mov_b32 m0, s61
	ds_read_b128 v[180:183], v147 offset:16384
	ds_read_b128 v[184:187], v147 offset:17408
	ds_read_b128 v[188:191], v147 offset:18432
	ds_read_b128 v[192:195], v147 offset:19456
	ds_read_b128 v[196:199], v147 offset:20480
	ds_read_b128 v[200:203], v147 offset:21504
	ds_read_b128 v[204:207], v147 offset:22528
	ds_read_b128 v[208:211], v147 offset:23552
	global_load_lds_dwordx4 v[142:143], off
	s_add_i32 m0, s61, 0x2000
	s_add_u32 s62, s40, 0x80000
	v_lshl_add_u64 v[212:213], s[40:41], 0, v[132:133]
	s_addc_u32 s63, s41, 0
	s_add_i32 s61, s64, s46
	global_load_lds_dwordx4 v[212:213], off
	v_lshl_add_u64 v[214:215], s[62:63], 0, v[34:35]
	s_mov_b32 m0, s61
	v_lshl_add_u64 v[216:217], s[42:43], 0, v[134:135]
	global_load_lds_dwordx4 v[214:215], off
	v_lshl_add_u64 v[214:215], s[62:63], 0, v[132:133]
	s_add_i32 m0, s61, 0x2000
	s_nop 0
	global_load_lds_dwordx4 v[214:215], off
	v_lshl_add_u64 v[214:215], s[42:43], 0, v[136:137]
	s_mov_b32 m0, s47
	s_nop 0
	global_load_lds_dwordx4 v[214:215], off
	s_mov_b32 m0, s48
	s_nop 0
	global_load_lds_dwordx4 v[216:217], off
	s_waitcnt vmcnt(8)
	s_waitcnt lgkmcnt(0)
	s_barrier
	s_setprio 1
	s_waitcnt lgkmcnt(0)
	v_mfma_f32_16x16x32_bf16 v[64:67], v[148:151], v[180:183], v[64:67]
	v_mfma_f32_16x16x32_bf16 v[60:63], v[156:159], v[180:183], v[60:63]
	v_mfma_f32_16x16x32_bf16 v[48:51], v[148:151], v[188:191], v[48:51]
	v_mfma_f32_16x16x32_bf16 v[44:47], v[156:159], v[188:191], v[44:47]
	v_mfma_f32_16x16x32_bf16 v[30:33], v[148:151], v[196:199], v[30:33]
	v_mfma_f32_16x16x32_bf16 v[26:29], v[156:159], v[196:199], v[26:29]
	v_mfma_f32_16x16x32_bf16 v[14:17], v[148:151], v[204:207], v[14:17]
	v_mfma_f32_16x16x32_bf16 v[10:13], v[156:159], v[204:207], v[10:13]
	v_mfma_f32_16x16x32_bf16 v[64:67], v[152:155], v[184:187], v[64:67]
	v_mfma_f32_16x16x32_bf16 v[60:63], v[160:163], v[184:187], v[60:63]
	v_mfma_f32_16x16x32_bf16 v[48:51], v[152:155], v[192:195], v[48:51]
	v_mfma_f32_16x16x32_bf16 v[44:47], v[160:163], v[192:195], v[44:47]
	v_mfma_f32_16x16x32_bf16 v[30:33], v[152:155], v[200:203], v[30:33]
	v_mfma_f32_16x16x32_bf16 v[26:29], v[160:163], v[200:203], v[26:29]
	v_mfma_f32_16x16x32_bf16 v[14:17], v[152:155], v[208:211], v[14:17]
	v_mfma_f32_16x16x32_bf16 v[10:13], v[160:163], v[208:211], v[10:13]
	v_mfma_f32_16x16x32_bf16 v[56:59], v[164:167], v[180:183], v[56:59]
	v_mfma_f32_16x16x32_bf16 v[52:55], v[172:175], v[180:183], v[52:55]
	v_mfma_f32_16x16x32_bf16 v[40:43], v[164:167], v[188:191], v[40:43]
	v_mfma_f32_16x16x32_bf16 v[36:39], v[172:175], v[188:191], v[36:39]
	v_mfma_f32_16x16x32_bf16 v[22:25], v[164:167], v[196:199], v[22:25]
	v_mfma_f32_16x16x32_bf16 v[18:21], v[172:175], v[196:199], v[18:21]
	v_mfma_f32_16x16x32_bf16 v[6:9], v[164:167], v[204:207], v[6:9]
	v_mfma_f32_16x16x32_bf16 v[2:5], v[172:175], v[204:207], v[2:5]
	v_mfma_f32_16x16x32_bf16 v[56:59], v[168:171], v[184:187], v[56:59]
	v_mfma_f32_16x16x32_bf16 v[52:55], v[176:179], v[184:187], v[52:55]
	v_mfma_f32_16x16x32_bf16 v[40:43], v[168:171], v[192:195], v[40:43]
	v_mfma_f32_16x16x32_bf16 v[36:39], v[176:179], v[192:195], v[36:39]
	v_mfma_f32_16x16x32_bf16 v[22:25], v[168:171], v[200:203], v[22:25]
	v_mfma_f32_16x16x32_bf16 v[18:21], v[176:179], v[200:203], v[18:21]
	v_mfma_f32_16x16x32_bf16 v[6:9], v[168:171], v[208:211], v[6:9]
	v_mfma_f32_16x16x32_bf16 v[2:5], v[176:179], v[208:211], v[2:5]
	s_setprio 0
	s_barrier
	s_add_i32 s61, 0, 0x18000
	s_add_i32 s62, 0, 0x1c000
	v_add_u32_e32 v160, s61, v145
	v_add_u32_e32 v176, s62, v145
	ds_read_b128 v[148:151], v160
	ds_read_b128 v[152:155], v160 offset:1024
	ds_read_b128 v[156:159], v160 offset:2048
	ds_read_b128 v[160:163], v160 offset:3072
	ds_read_b128 v[164:167], v176
	ds_read_b128 v[168:171], v176 offset:1024
	ds_read_b128 v[172:175], v176 offset:2048
	ds_read_b128 v[176:179], v176 offset:3072
	s_add_u32 s42, s42, 0x80000
	s_addc_u32 s43, s43, 0
	s_mov_b32 m0, s49
	v_lshl_add_u64 v[218:219], s[42:43], 0, v[136:137]
	ds_read_b128 v[180:183], v147 offset:32768
	ds_read_b128 v[184:187], v147 offset:33792
	ds_read_b128 v[188:191], v147 offset:34816
	ds_read_b128 v[192:195], v147 offset:35840
	ds_read_b128 v[196:199], v147 offset:36864
	ds_read_b128 v[200:203], v147 offset:37888
	ds_read_b128 v[204:207], v147 offset:38912
	ds_read_b128 v[208:211], v147 offset:39936
	global_load_lds_dwordx4 v[218:219], off
	v_lshl_add_u64 v[218:219], s[42:43], 0, v[134:135]
	s_mov_b32 m0, s50
	s_nop 0
	global_load_lds_dwordx4 v[218:219], off
	s_waitcnt vmcnt(8)
	s_waitcnt lgkmcnt(0)
	s_barrier
	s_setprio 1
	s_waitcnt lgkmcnt(0)
	v_mfma_f32_16x16x32_bf16 v[128:131], v[148:151], v[180:183], v[128:131]
	v_mfma_f32_16x16x32_bf16 v[124:127], v[156:159], v[180:183], v[124:127]
	v_mfma_f32_16x16x32_bf16 v[112:115], v[148:151], v[188:191], v[112:115]
	v_mfma_f32_16x16x32_bf16 v[108:111], v[156:159], v[188:191], v[108:111]
	v_mfma_f32_16x16x32_bf16 v[96:99], v[148:151], v[196:199], v[96:99]
	v_mfma_f32_16x16x32_bf16 v[92:95], v[156:159], v[196:199], v[92:95]
	v_mfma_f32_16x16x32_bf16 v[80:83], v[148:151], v[204:207], v[80:83]
	v_mfma_f32_16x16x32_bf16 v[76:79], v[156:159], v[204:207], v[76:79]
	v_mfma_f32_16x16x32_bf16 v[128:131], v[152:155], v[184:187], v[128:131]
	v_mfma_f32_16x16x32_bf16 v[124:127], v[160:163], v[184:187], v[124:127]
	v_mfma_f32_16x16x32_bf16 v[112:115], v[152:155], v[192:195], v[112:115]
	v_mfma_f32_16x16x32_bf16 v[108:111], v[160:163], v[192:195], v[108:111]
	v_mfma_f32_16x16x32_bf16 v[96:99], v[152:155], v[200:203], v[96:99]
	v_mfma_f32_16x16x32_bf16 v[92:95], v[160:163], v[200:203], v[92:95]
	v_mfma_f32_16x16x32_bf16 v[80:83], v[152:155], v[208:211], v[80:83]
	v_mfma_f32_16x16x32_bf16 v[76:79], v[160:163], v[208:211], v[76:79]
	v_mfma_f32_16x16x32_bf16 v[120:123], v[164:167], v[180:183], v[120:123]
	v_mfma_f32_16x16x32_bf16 v[116:119], v[172:175], v[180:183], v[116:119]
	v_mfma_f32_16x16x32_bf16 v[104:107], v[164:167], v[188:191], v[104:107]
	v_mfma_f32_16x16x32_bf16 v[100:103], v[172:175], v[188:191], v[100:103]
	v_mfma_f32_16x16x32_bf16 v[88:91], v[164:167], v[196:199], v[88:91]
	v_mfma_f32_16x16x32_bf16 v[84:87], v[172:175], v[196:199], v[84:87]
	v_mfma_f32_16x16x32_bf16 v[72:75], v[164:167], v[204:207], v[72:75]
	v_mfma_f32_16x16x32_bf16 v[68:71], v[172:175], v[204:207], v[68:71]
	v_mfma_f32_16x16x32_bf16 v[120:123], v[168:171], v[184:187], v[120:123]
	v_mfma_f32_16x16x32_bf16 v[116:119], v[176:179], v[184:187], v[116:119]
	v_mfma_f32_16x16x32_bf16 v[104:107], v[168:171], v[192:195], v[104:107]
	v_mfma_f32_16x16x32_bf16 v[100:103], v[176:179], v[192:195], v[100:103]
	v_mfma_f32_16x16x32_bf16 v[88:91], v[168:171], v[200:203], v[88:91]
	v_mfma_f32_16x16x32_bf16 v[84:87], v[176:179], v[200:203], v[84:87]
	v_mfma_f32_16x16x32_bf16 v[72:75], v[168:171], v[208:211], v[72:75]
	v_mfma_f32_16x16x32_bf16 v[68:71], v[176:179], v[208:211], v[68:71]
	s_setprio 0
	s_barrier
	s_add_i32 s42, s61, s46
	v_lshl_add_u64 v[142:143], v[142:143], 0, s[96:97]
	s_mov_b32 m0, s42
	ds_read_b128 v[180:183], v147 offset:49152
	ds_read_b128 v[184:187], v147 offset:50176
	ds_read_b128 v[188:191], v147 offset:51200
	ds_read_b128 v[192:195], v147 offset:52224
	ds_read_b128 v[196:199], v147 offset:53248
	ds_read_b128 v[200:203], v147 offset:54272
	ds_read_b128 v[204:207], v147 offset:55296
	ds_read_b128 v[208:211], v147 offset:56320
	global_load_lds_dwordx4 v[142:143], off
	s_add_i32 m0, s42, 0x2000
	s_add_u32 s40, s40, 0x80080
	v_lshl_add_u64 v[142:143], v[212:213], 0, s[96:97]
	s_addc_u32 s41, s41, 0
	s_add_i32 s42, s62, s46
	global_load_lds_dwordx4 v[142:143], off
	v_lshl_add_u64 v[142:143], s[40:41], 0, v[34:35]
	s_mov_b32 m0, s42
	s_nop 0
	global_load_lds_dwordx4 v[142:143], off
	v_lshl_add_u64 v[142:143], s[40:41], 0, v[132:133]
	s_add_i32 m0, s42, 0x2000
	s_nop 0
	global_load_lds_dwordx4 v[142:143], off
	v_lshl_add_u64 v[142:143], v[214:215], 0, s[96:97]
	s_mov_b32 m0, s51
	s_nop 0
	global_load_lds_dwordx4 v[142:143], off
	v_lshl_add_u64 v[142:143], v[216:217], 0, s[96:97]
	s_mov_b32 m0, s52
	s_nop 0
	global_load_lds_dwordx4 v[142:143], off
	s_waitcnt vmcnt(8)
	s_waitcnt lgkmcnt(0)
	s_barrier
	s_setprio 1
	s_waitcnt lgkmcnt(0)
	v_mfma_f32_16x16x32_bf16 v[64:67], v[148:151], v[180:183], v[64:67]
	v_mfma_f32_16x16x32_bf16 v[60:63], v[156:159], v[180:183], v[60:63]
	v_mfma_f32_16x16x32_bf16 v[48:51], v[148:151], v[188:191], v[48:51]
	v_mfma_f32_16x16x32_bf16 v[44:47], v[156:159], v[188:191], v[44:47]
	v_mfma_f32_16x16x32_bf16 v[30:33], v[148:151], v[196:199], v[30:33]
	v_mfma_f32_16x16x32_bf16 v[26:29], v[156:159], v[196:199], v[26:29]
	v_mfma_f32_16x16x32_bf16 v[14:17], v[148:151], v[204:207], v[14:17]
	v_mfma_f32_16x16x32_bf16 v[10:13], v[156:159], v[204:207], v[10:13]
	v_mfma_f32_16x16x32_bf16 v[64:67], v[152:155], v[184:187], v[64:67]
	v_mfma_f32_16x16x32_bf16 v[60:63], v[160:163], v[184:187], v[60:63]
	v_mfma_f32_16x16x32_bf16 v[48:51], v[152:155], v[192:195], v[48:51]
	v_mfma_f32_16x16x32_bf16 v[44:47], v[160:163], v[192:195], v[44:47]
	v_mfma_f32_16x16x32_bf16 v[30:33], v[152:155], v[200:203], v[30:33]
	v_mfma_f32_16x16x32_bf16 v[26:29], v[160:163], v[200:203], v[26:29]
	v_mfma_f32_16x16x32_bf16 v[14:17], v[152:155], v[208:211], v[14:17]
	v_mfma_f32_16x16x32_bf16 v[10:13], v[160:163], v[208:211], v[10:13]
	v_mfma_f32_16x16x32_bf16 v[56:59], v[164:167], v[180:183], v[56:59]
	v_mfma_f32_16x16x32_bf16 v[52:55], v[172:175], v[180:183], v[52:55]
	v_mfma_f32_16x16x32_bf16 v[40:43], v[164:167], v[188:191], v[40:43]
	v_mfma_f32_16x16x32_bf16 v[36:39], v[172:175], v[188:191], v[36:39]
	v_mfma_f32_16x16x32_bf16 v[22:25], v[164:167], v[196:199], v[22:25]
	v_mfma_f32_16x16x32_bf16 v[18:21], v[172:175], v[196:199], v[18:21]
	v_mfma_f32_16x16x32_bf16 v[6:9], v[164:167], v[204:207], v[6:9]
	v_mfma_f32_16x16x32_bf16 v[2:5], v[172:175], v[204:207], v[2:5]
	v_mfma_f32_16x16x32_bf16 v[56:59], v[168:171], v[184:187], v[56:59]
	v_mfma_f32_16x16x32_bf16 v[52:55], v[176:179], v[184:187], v[52:55]
	v_mfma_f32_16x16x32_bf16 v[40:43], v[168:171], v[192:195], v[40:43]
	v_mfma_f32_16x16x32_bf16 v[36:39], v[176:179], v[192:195], v[36:39]
	v_mfma_f32_16x16x32_bf16 v[22:25], v[168:171], v[200:203], v[22:25]
	v_mfma_f32_16x16x32_bf16 v[18:21], v[176:179], v[200:203], v[18:21]
	v_mfma_f32_16x16x32_bf16 v[6:9], v[168:171], v[208:211], v[6:9]
	v_mfma_f32_16x16x32_bf16 v[2:5], v[176:179], v[208:211], v[2:5]
	s_setprio 0
	s_barrier
	s_add_i32 s60, s60, 2
	s_add_u32 s18, s18, 0x100
	s_addc_u32 s19, s19, 0
	s_add_u32 s58, s58, 0x100
	s_addc_u32 s59, s59, 0
	s_cmp_gt_u32 s60, 29
	s_cbranch_scc0 .LBB0_1485
	s_and_b64 vcc, exec, s[6:7]
	s_cbranch_vccz .LBB0_1488
	s_barrier

.LBB0_1577:
	s_add_u32 s41, s8, s50
	s_addc_u32 s43, s9, s51
	s_add_u32 s52, s10, s50
	s_addc_u32 s53, s11, s51
	s_cmp_eq_u32 s58, s19
	s_cselect_b32 s55, s47, s43
	s_cselect_b32 s54, s46, s41
	s_cselect_b32 s53, s49, s53
	s_cselect_b32 s52, s48, s52
	s_add_i32 s41, 0, 0x10000
	s_add_i32 s43, 0, 0x14000
	v_add_u32_e32 v154, s41, v185
	v_add_u32_e32 v170, s43, v185
	ds_read_b128 v[136:139], v154
	ds_read_b128 v[140:143], v154 offset:1024
	ds_read_b128 v[144:147], v154 offset:2048
	ds_read_b128 v[154:157], v154 offset:3072
	ds_read_b128 v[158:161], v170
	ds_read_b128 v[162:165], v170 offset:1024
	ds_read_b128 v[166:169], v170 offset:2048
	ds_read_b128 v[170:173], v170 offset:3072
	v_lshl_add_u64 v[182:183], s[8:9], 0, v[134:135]
	s_add_i32 m0, s1, 0xc000
	ds_read_b128 v[174:177], v199
	ds_read_b128 v[178:181], v199 offset:1024
	ds_read_b128 v[186:189], v199 offset:2048
	ds_read_b128 v[190:193], v199 offset:3072
	ds_read_b128 v[194:197], v199 offset:4096
	ds_read_b128 v[200:203], v199 offset:5120
	ds_read_b128 v[204:207], v199 offset:6144
	ds_read_b128 v[208:211], v199 offset:7168
	global_load_lds_dwordx4 v[182:183], off
	v_lshl_add_u64 v[182:183], s[8:9], 0, v[132:133]
	s_add_i32 m0, s1, 0xe000
	s_nop 0
	global_load_lds_dwordx4 v[182:183], off
	s_waitcnt vmcnt(8)
	s_waitcnt lgkmcnt(0)
	s_barrier
	s_setprio 1
	s_waitcnt lgkmcnt(0)
	v_mfma_f32_16x16x32_bf16 v[128:131], v[136:139], v[174:177], v[128:131]
	v_mfma_f32_16x16x32_bf16 v[124:127], v[144:147], v[174:177], v[124:127]
	v_mfma_f32_16x16x32_bf16 v[120:123], v[136:139], v[186:189], v[120:123]
	v_mfma_f32_16x16x32_bf16 v[116:119], v[144:147], v[186:189], v[116:119]
	v_mfma_f32_16x16x32_bf16 v[112:115], v[136:139], v[194:197], v[112:115]
	v_mfma_f32_16x16x32_bf16 v[108:111], v[144:147], v[194:197], v[108:111]
	v_mfma_f32_16x16x32_bf16 v[104:107], v[136:139], v[204:207], v[104:107]
	v_mfma_f32_16x16x32_bf16 v[100:103], v[144:147], v[204:207], v[100:103]
	v_mfma_f32_16x16x32_bf16 v[128:131], v[140:143], v[178:181], v[128:131]
	v_mfma_f32_16x16x32_bf16 v[124:127], v[154:157], v[178:181], v[124:127]
	v_mfma_f32_16x16x32_bf16 v[120:123], v[140:143], v[190:193], v[120:123]
	v_mfma_f32_16x16x32_bf16 v[116:119], v[154:157], v[190:193], v[116:119]
	v_mfma_f32_16x16x32_bf16 v[112:115], v[140:143], v[200:203], v[112:115]
	v_mfma_f32_16x16x32_bf16 v[108:111], v[154:157], v[200:203], v[108:111]
	v_mfma_f32_16x16x32_bf16 v[104:107], v[140:143], v[208:211], v[104:107]
	v_mfma_f32_16x16x32_bf16 v[100:103], v[154:157], v[208:211], v[100:103]
	v_mfma_f32_16x16x32_bf16 v[96:99], v[158:161], v[174:177], v[96:99]
	v_mfma_f32_16x16x32_bf16 v[92:95], v[166:169], v[174:177], v[92:95]
	v_mfma_f32_16x16x32_bf16 v[88:91], v[158:161], v[186:189], v[88:91]
	v_mfma_f32_16x16x32_bf16 v[84:87], v[166:169], v[186:189], v[84:87]
	v_mfma_f32_16x16x32_bf16 v[80:83], v[158:161], v[194:197], v[80:83]
	v_mfma_f32_16x16x32_bf16 v[76:79], v[166:169], v[194:197], v[76:79]
	v_mfma_f32_16x16x32_bf16 v[72:75], v[158:161], v[204:207], v[72:75]
	v_mfma_f32_16x16x32_bf16 v[68:71], v[166:169], v[204:207], v[68:71]
	v_mfma_f32_16x16x32_bf16 v[96:99], v[162:165], v[178:181], v[96:99]
	v_mfma_f32_16x16x32_bf16 v[92:95], v[170:173], v[178:181], v[92:95]
	v_mfma_f32_16x16x32_bf16 v[88:91], v[162:165], v[190:193], v[88:91]
	v_mfma_f32_16x16x32_bf16 v[84:87], v[170:173], v[190:193], v[84:87]
	v_mfma_f32_16x16x32_bf16 v[80:83], v[162:165], v[200:203], v[80:83]
	v_mfma_f32_16x16x32_bf16 v[76:79], v[170:173], v[200:203], v[76:79]
	v_mfma_f32_16x16x32_bf16 v[72:75], v[162:165], v[208:211], v[72:75]
	v_mfma_f32_16x16x32_bf16 v[68:71], v[170:173], v[208:211], v[68:71]
	s_setprio 0
	s_barrier
	s_add_i32 s41, s41, s59
	v_lshl_add_u64 v[182:183], s[52:53], 0, v[34:35]
	s_mov_b32 m0, s41
	ds_read_b128 v[174:177], v199 offset:16384
	ds_read_b128 v[178:181], v199 offset:17408
	ds_read_b128 v[186:189], v199 offset:18432
	ds_read_b128 v[190:193], v199 offset:19456
	ds_read_b128 v[194:197], v199 offset:20480
	ds_read_b128 v[200:203], v199 offset:21504
	ds_read_b128 v[204:207], v199 offset:22528
	ds_read_b128 v[208:211], v199 offset:23552
	global_load_lds_dwordx4 v[182:183], off
	s_add_i32 m0, s41, 0x2000
	s_add_u32 s70, s52, 0x200000
	v_lshl_add_u64 v[212:213], s[52:53], 0, v[148:149]
	s_addc_u32 s71, s53, 0
	s_add_i32 s41, s43, s59
	global_load_lds_dwordx4 v[212:213], off
	v_lshl_add_u64 v[214:215], s[70:71], 0, v[34:35]
	s_mov_b32 m0, s41
	v_lshl_add_u64 v[216:217], s[54:55], 0, v[148:149]
	global_load_lds_dwordx4 v[214:215], off
	v_lshl_add_u64 v[214:215], s[70:71], 0, v[148:149]
	s_add_i32 m0, s41, 0x2000
	s_nop 0
	global_load_lds_dwordx4 v[214:215], off
	v_lshl_add_u64 v[214:215], s[54:55], 0, v[34:35]
	s_mov_b32 m0, s1
	s_nop 0
	global_load_lds_dwordx4 v[214:215], off
	s_mov_b32 m0, s7
	s_nop 0
	global_load_lds_dwordx4 v[216:217], off
	s_waitcnt vmcnt(8)
	s_waitcnt lgkmcnt(0)
	s_barrier
	s_setprio 1
	s_waitcnt lgkmcnt(0)
	v_mfma_f32_16x16x32_bf16 v[64:67], v[136:139], v[174:177], v[64:67]
	v_mfma_f32_16x16x32_bf16 v[60:63], v[144:147], v[174:177], v[60:63]
	v_mfma_f32_16x16x32_bf16 v[56:59], v[136:139], v[186:189], v[56:59]
	v_mfma_f32_16x16x32_bf16 v[52:55], v[144:147], v[186:189], v[52:55]
	v_mfma_f32_16x16x32_bf16 v[48:51], v[136:139], v[194:197], v[48:51]
	v_mfma_f32_16x16x32_bf16 v[44:47], v[144:147], v[194:197], v[44:47]
	v_mfma_f32_16x16x32_bf16 v[40:43], v[136:139], v[204:207], v[40:43]
	v_mfma_f32_16x16x32_bf16 v[36:39], v[144:147], v[204:207], v[36:39]
	v_mfma_f32_16x16x32_bf16 v[64:67], v[140:143], v[178:181], v[64:67]
	v_mfma_f32_16x16x32_bf16 v[60:63], v[154:157], v[178:181], v[60:63]
	v_mfma_f32_16x16x32_bf16 v[56:59], v[140:143], v[190:193], v[56:59]
	v_mfma_f32_16x16x32_bf16 v[52:55], v[154:157], v[190:193], v[52:55]
	v_mfma_f32_16x16x32_bf16 v[48:51], v[140:143], v[200:203], v[48:51]
	v_mfma_f32_16x16x32_bf16 v[44:47], v[154:157], v[200:203], v[44:47]
	v_mfma_f32_16x16x32_bf16 v[40:43], v[140:143], v[208:211], v[40:43]
	v_mfma_f32_16x16x32_bf16 v[36:39], v[154:157], v[208:211], v[36:39]
	v_mfma_f32_16x16x32_bf16 v[30:33], v[158:161], v[174:177], v[30:33]
	v_mfma_f32_16x16x32_bf16 v[26:29], v[166:169], v[174:177], v[26:29]
	v_mfma_f32_16x16x32_bf16 v[22:25], v[158:161], v[186:189], v[22:25]
	v_mfma_f32_16x16x32_bf16 v[18:21], v[166:169], v[186:189], v[18:21]
	v_mfma_f32_16x16x32_bf16 v[14:17], v[158:161], v[194:197], v[14:17]
	v_mfma_f32_16x16x32_bf16 v[10:13], v[166:169], v[194:197], v[10:13]
	v_mfma_f32_16x16x32_bf16 v[6:9], v[158:161], v[204:207], v[6:9]
	v_mfma_f32_16x16x32_bf16 v[2:5], v[166:169], v[204:207], v[2:5]
	v_mfma_f32_16x16x32_bf16 v[30:33], v[162:165], v[178:181], v[30:33]
	v_mfma_f32_16x16x32_bf16 v[26:29], v[170:173], v[178:181], v[26:29]
	v_mfma_f32_16x16x32_bf16 v[22:25], v[162:165], v[190:193], v[22:25]
	v_mfma_f32_16x16x32_bf16 v[18:21], v[170:173], v[190:193], v[18:21]
	v_mfma_f32_16x16x32_bf16 v[14:17], v[162:165], v[200:203], v[14:17]
	v_mfma_f32_16x16x32_bf16 v[10:13], v[170:173], v[200:203], v[10:13]
	v_mfma_f32_16x16x32_bf16 v[6:9], v[162:165], v[208:211], v[6:9]
	v_mfma_f32_16x16x32_bf16 v[2:5], v[170:173], v[208:211], v[2:5]
	s_setprio 0
	s_barrier
	s_add_i32 s41, 0, 0x18000
	s_add_i32 s43, 0, 0x1c000
	v_add_u32_e32 v154, s41, v185
	v_add_u32_e32 v170, s43, v185
	ds_read_b128 v[136:139], v154
	ds_read_b128 v[140:143], v154 offset:1024
	ds_read_b128 v[144:147], v154 offset:2048
	ds_read_b128 v[154:157], v154 offset:3072
	ds_read_b128 v[158:161], v170
	ds_read_b128 v[162:165], v170 offset:1024
	ds_read_b128 v[166:169], v170 offset:2048
	ds_read_b128 v[170:173], v170 offset:3072
	s_add_u32 s54, s54, 0x200000
	s_addc_u32 s55, s55, 0
	s_mov_b32 m0, s62
	v_lshl_add_u64 v[218:219], s[54:55], 0, v[34:35]
	ds_read_b128 v[174:177], v199 offset:32768
	ds_read_b128 v[178:181], v199 offset:33792
	ds_read_b128 v[186:189], v199 offset:34816
	ds_read_b128 v[190:193], v199 offset:35840
	ds_read_b128 v[194:197], v199 offset:36864
	ds_read_b128 v[200:203], v199 offset:37888
	ds_read_b128 v[204:207], v199 offset:38912
	ds_read_b128 v[208:211], v199 offset:39936
	global_load_lds_dwordx4 v[218:219], off
	v_lshl_add_u64 v[218:219], s[54:55], 0, v[148:149]
	s_mov_b32 m0, s63
	s_nop 0
	global_load_lds_dwordx4 v[218:219], off
	s_waitcnt vmcnt(8)
	s_waitcnt lgkmcnt(0)
	s_barrier
	s_setprio 1
	s_waitcnt lgkmcnt(0)
	v_mfma_f32_16x16x32_bf16 v[128:131], v[136:139], v[174:177], v[128:131]
	v_mfma_f32_16x16x32_bf16 v[124:127], v[144:147], v[174:177], v[124:127]
	v_mfma_f32_16x16x32_bf16 v[120:123], v[136:139], v[186:189], v[120:123]
	v_mfma_f32_16x16x32_bf16 v[116:119], v[144:147], v[186:189], v[116:119]
	v_mfma_f32_16x16x32_bf16 v[112:115], v[136:139], v[194:197], v[112:115]
	v_mfma_f32_16x16x32_bf16 v[108:111], v[144:147], v[194:197], v[108:111]
	v_mfma_f32_16x16x32_bf16 v[104:107], v[136:139], v[204:207], v[104:107]
	v_mfma_f32_16x16x32_bf16 v[100:103], v[144:147], v[204:207], v[100:103]
	v_mfma_f32_16x16x32_bf16 v[128:131], v[140:143], v[178:181], v[128:131]
	v_mfma_f32_16x16x32_bf16 v[124:127], v[154:157], v[178:181], v[124:127]
	v_mfma_f32_16x16x32_bf16 v[120:123], v[140:143], v[190:193], v[120:123]
	v_mfma_f32_16x16x32_bf16 v[116:119], v[154:157], v[190:193], v[116:119]
	v_mfma_f32_16x16x32_bf16 v[112:115], v[140:143], v[200:203], v[112:115]
	v_mfma_f32_16x16x32_bf16 v[108:111], v[154:157], v[200:203], v[108:111]
	v_mfma_f32_16x16x32_bf16 v[104:107], v[140:143], v[208:211], v[104:107]
	v_mfma_f32_16x16x32_bf16 v[100:103], v[154:157], v[208:211], v[100:103]
	v_mfma_f32_16x16x32_bf16 v[96:99], v[158:161], v[174:177], v[96:99]
	v_mfma_f32_16x16x32_bf16 v[92:95], v[166:169], v[174:177], v[92:95]
	v_mfma_f32_16x16x32_bf16 v[88:91], v[158:161], v[186:189], v[88:91]
	v_mfma_f32_16x16x32_bf16 v[84:87], v[166:169], v[186:189], v[84:87]
	v_mfma_f32_16x16x32_bf16 v[80:83], v[158:161], v[194:197], v[80:83]
	v_mfma_f32_16x16x32_bf16 v[76:79], v[166:169], v[194:197], v[76:79]
	v_mfma_f32_16x16x32_bf16 v[72:75], v[158:161], v[204:207], v[72:75]
	v_mfma_f32_16x16x32_bf16 v[68:71], v[166:169], v[204:207], v[68:71]
	v_mfma_f32_16x16x32_bf16 v[96:99], v[162:165], v[178:181], v[96:99]
	v_mfma_f32_16x16x32_bf16 v[92:95], v[170:173], v[178:181], v[92:95]
	v_mfma_f32_16x16x32_bf16 v[88:91], v[162:165], v[190:193], v[88:91]
	v_mfma_f32_16x16x32_bf16 v[84:87], v[170:173], v[190:193], v[84:87]
	v_mfma_f32_16x16x32_bf16 v[80:83], v[162:165], v[200:203], v[80:83]
	v_mfma_f32_16x16x32_bf16 v[76:79], v[170:173], v[200:203], v[76:79]
	v_mfma_f32_16x16x32_bf16 v[72:75], v[162:165], v[208:211], v[72:75]
	v_mfma_f32_16x16x32_bf16 v[68:71], v[170:173], v[208:211], v[68:71]
	s_setprio 0
	s_barrier
	s_add_i32 s41, s41, s59
	v_lshl_add_u64 v[182:183], v[182:183], 0, s[96:97]
	s_mov_b32 m0, s41
	ds_read_b128 v[174:177], v199 offset:49152
	ds_read_b128 v[178:181], v199 offset:50176
	ds_read_b128 v[186:189], v199 offset:51200
	ds_read_b128 v[190:193], v199 offset:52224
	ds_read_b128 v[194:197], v199 offset:53248
	ds_read_b128 v[200:203], v199 offset:54272
	ds_read_b128 v[204:207], v199 offset:55296
	ds_read_b128 v[208:211], v199 offset:56320
	global_load_lds_dwordx4 v[182:183], off
	s_add_i32 m0, s41, 0x2000
	s_add_u32 s52, s52, 0x200080
	v_lshl_add_u64 v[182:183], v[212:213], 0, s[96:97]
	s_addc_u32 s53, s53, 0
	s_add_i32 s41, s43, s59
	global_load_lds_dwordx4 v[182:183], off
	v_lshl_add_u64 v[182:183], s[52:53], 0, v[34:35]
	s_mov_b32 m0, s41
	s_nop 0
	global_load_lds_dwordx4 v[182:183], off
	v_lshl_add_u64 v[182:183], s[52:53], 0, v[148:149]
	s_add_i32 m0, s41, 0x2000
	s_nop 0
	global_load_lds_dwordx4 v[182:183], off
	v_lshl_add_u64 v[182:183], v[214:215], 0, s[96:97]
	s_mov_b32 m0, s64
	s_nop 0
	global_load_lds_dwordx4 v[182:183], off
	v_lshl_add_u64 v[182:183], v[216:217], 0, s[96:97]
	s_mov_b32 m0, s65
	s_nop 0
	global_load_lds_dwordx4 v[182:183], off
	s_waitcnt vmcnt(8)
	s_waitcnt lgkmcnt(0)
	s_barrier
	s_setprio 1
	s_waitcnt lgkmcnt(0)
	v_mfma_f32_16x16x32_bf16 v[64:67], v[136:139], v[174:177], v[64:67]
	v_mfma_f32_16x16x32_bf16 v[60:63], v[144:147], v[174:177], v[60:63]
	v_mfma_f32_16x16x32_bf16 v[56:59], v[136:139], v[186:189], v[56:59]
	v_mfma_f32_16x16x32_bf16 v[52:55], v[144:147], v[186:189], v[52:55]
	v_mfma_f32_16x16x32_bf16 v[48:51], v[136:139], v[194:197], v[48:51]
	v_mfma_f32_16x16x32_bf16 v[44:47], v[144:147], v[194:197], v[44:47]
	v_mfma_f32_16x16x32_bf16 v[40:43], v[136:139], v[204:207], v[40:43]
	v_mfma_f32_16x16x32_bf16 v[36:39], v[144:147], v[204:207], v[36:39]
	v_mfma_f32_16x16x32_bf16 v[64:67], v[140:143], v[178:181], v[64:67]
	v_mfma_f32_16x16x32_bf16 v[60:63], v[154:157], v[178:181], v[60:63]
	v_mfma_f32_16x16x32_bf16 v[56:59], v[140:143], v[190:193], v[56:59]
	v_mfma_f32_16x16x32_bf16 v[52:55], v[154:157], v[190:193], v[52:55]
	v_mfma_f32_16x16x32_bf16 v[48:51], v[140:143], v[200:203], v[48:51]
	v_mfma_f32_16x16x32_bf16 v[44:47], v[154:157], v[200:203], v[44:47]
	v_mfma_f32_16x16x32_bf16 v[40:43], v[140:143], v[208:211], v[40:43]
	v_mfma_f32_16x16x32_bf16 v[36:39], v[154:157], v[208:211], v[36:39]
	v_mfma_f32_16x16x32_bf16 v[30:33], v[158:161], v[174:177], v[30:33]
	v_mfma_f32_16x16x32_bf16 v[26:29], v[166:169], v[174:177], v[26:29]
	v_mfma_f32_16x16x32_bf16 v[22:25], v[158:161], v[186:189], v[22:25]
	v_mfma_f32_16x16x32_bf16 v[18:21], v[166:169], v[186:189], v[18:21]
	v_mfma_f32_16x16x32_bf16 v[14:17], v[158:161], v[194:197], v[14:17]
	v_mfma_f32_16x16x32_bf16 v[10:13], v[166:169], v[194:197], v[10:13]
	v_mfma_f32_16x16x32_bf16 v[6:9], v[158:161], v[204:207], v[6:9]
	v_mfma_f32_16x16x32_bf16 v[2:5], v[166:169], v[204:207], v[2:5]
	v_mfma_f32_16x16x32_bf16 v[30:33], v[162:165], v[178:181], v[30:33]
	v_mfma_f32_16x16x32_bf16 v[26:29], v[170:173], v[178:181], v[26:29]
	v_mfma_f32_16x16x32_bf16 v[22:25], v[162:165], v[190:193], v[22:25]
	v_mfma_f32_16x16x32_bf16 v[18:21], v[170:173], v[190:193], v[18:21]
	v_mfma_f32_16x16x32_bf16 v[14:17], v[162:165], v[200:203], v[14:17]
	v_mfma_f32_16x16x32_bf16 v[10:13], v[170:173], v[200:203], v[10:13]
	v_mfma_f32_16x16x32_bf16 v[6:9], v[162:165], v[208:211], v[6:9]
	v_mfma_f32_16x16x32_bf16 v[2:5], v[170:173], v[208:211], v[2:5]
	s_setprio 0
	s_barrier
	s_add_i32 s41, s19, 2
	s_add_u32 s50, s50, 0x100
	s_addc_u32 s51, s51, 0
	v_lshl_add_u64 v[134:135], v[134:135], 0, s[28:29]
	v_lshl_add_u64 v[132:133], v[132:133], 0, s[28:29]
	s_cmp_ge_i32 s19, s58
	s_mov_b32 s19, s41
	s_cbranch_scc0 .LBB0_1577
	s_and_b64 vcc, exec, s[16:17]
	s_cbranch_vccz .LBB0_1580
	s_barrier
